# v075 + rwkv_p1 groups remapped so XCD x prepares batch x (the rows it produced in the input projection); k0->k1 grid barriers of both layers become XCD-local (5 local barriers in all)
# speedup vs baseline: 1.0133x; 1.0133x over previous
; __device__ __forceinline__ void rwkv_p1(const KA& A, const Ctx& F, int l) {
;     ...
;     for (int grp = F.bid; grp < RW_ITEMS / 6; grp += F.G) {
;       const int j = grp & 63, b = grp >> 6;
;       const size_t row0 = (size_t)b * SEQ + 64 * j;
;       bf16x8_t xf[8];
;       { const int tt = w & 1; const size_t grow = row0 + 32 * tt + r32; const bool first = (j == 0) && (tt == 0) && (r32 == 0);
;         LoraRaw lr[8];
; #pragma unroll
;         for (int s = 0; s < 8; ++s) { const int jc = (w < 4) ? (128 + 16 * s + 8 * hh) : ((s < 4) ? (16 * s + 8 * hh) : (64 + 16 * (s - 4) + 8 * hh)); lr[s] = lora_load(PS, grow, first, jc, mix); }
; #pragma unroll
;         for (int s = 0; s < 8; ++s) asm volatile("" :: "v"(lr[s].c), "v"(lr[s].p), "v"(lr[s].m0), "v"(lr[s].m1));
.LBB0_388:
	s_and_b32 s0, s80, 7
	s_bfe_u32 s2, s80, 0x50003
	s_lshr_b32 s1, s80, 8
	s_lshl_b32 s1, s1, 5
	s_or_b32 s2, s2, s1
	s_ashr_i32 s1, s0, 31
	s_lshl_b64 s[4:5], s[0:1], 12
	s_lshl_b32 s1, s2, 6
	s_or_b32 s1, s4, s1
	v_or_b32_e32 v0, s52, v112
	v_writelane_b32 v255, s1, 33
	v_or_b32_e32 v4, s1, v0
	v_readlane_b32 s1, v254, 31
	v_writelane_b32 v254, s2, 0
	v_mov_b32_e32 v5, s5
	v_or_b32_e32 v0, s1, v112
	v_or_b32_e32 v6, s2, v0
	v_mov_b64_e32 v[0:1], s[82:83]
	v_mad_u64_u32 v[2:3], s[2:3], v4, s92, v[0:1]
	v_cmp_ne_u32_e64 s[2:3], 0, v6
	s_mov_b32 s1, s5
	v_writelane_b32 v255, s0, 34
	v_cndmask_b32_e64 v6, 0, 1, s[2:3]
	v_sub_co_u32_e32 v4, vcc, v4, v6
	v_writelane_b32 v255, s1, 35
	v_mad_i32_i24 v3, s5, v236, v3
	v_mad_u64_u32 v[0:1], s[4:5], v4, s92, v[0:1]
	v_lshlrev_b32_e32 v8, 3, v110
	v_readlane_b32 s4, v255, 14
	v_subbrev_co_u32_e32 v5, vcc, 0, v5, vcc
	v_add_u32_e32 v4, 0x80, v8
	v_readlane_b32 s5, v255, 15
	s_mov_b64 s[6:7], 0x1200
	v_mad_i32_i24 v1, v5, s92, v1
	v_cndmask_b32_e64 v80, v8, v4, s[4:5]
	v_lshl_add_u64 v[2:3], v[2:3], 0, s[6:7]
	v_lshl_add_u64 v[0:1], v[0:1], 0, s[6:7]
	v_lshlrev_b32_e32 v4, 1, v80
	v_mov_b32_e32 v5, v81
	v_readlane_b32 s4, v254, 13
	v_lshl_add_u64 v[6:7], v[2:3], 0, v[4:5]
	v_lshl_add_u64 v[4:5], v[0:1], 0, v[4:5]
	v_readlane_b32 s5, v254, 14
	v_readlane_b32 s1, v255, 16
	global_load_dwordx4 v[48:51], v[6:7], off
	global_load_dwordx4 v[52:55], v[4:5], off
	v_lshl_add_u64 v[4:5], v[80:81], 2, s[4:5]
	v_add_u32_e32 v80, s1, v8
	global_load_dwordx4 v[94:97], v[4:5], off offset:16
	global_load_dwordx4 v[98:101], v[4:5], off
	v_lshlrev_b32_e32 v4, 1, v80
	v_mov_b32_e32 v5, v81
	v_lshl_add_u64 v[6:7], v[2:3], 0, v[4:5]
	v_lshl_add_u64 v[4:5], v[0:1], 0, v[4:5]
	v_readlane_b32 s1, v255, 17
	global_load_dwordx4 v[56:59], v[6:7], off
	global_load_dwordx4 v[60:63], v[4:5], off
	v_lshl_add_u64 v[4:5], v[80:81], 2, s[4:5]
	v_add_u32_e32 v80, s1, v8
	global_load_dwordx4 v[86:89], v[4:5], off offset:16
	global_load_dwordx4 v[90:93], v[4:5], off
	v_lshlrev_b32_e32 v4, 1, v80
	v_mov_b32_e32 v5, v81
	v_lshl_add_u64 v[6:7], v[2:3], 0, v[4:5]
	v_lshl_add_u64 v[4:5], v[0:1], 0, v[4:5]
	v_readlane_b32 s1, v255, 18
	global_load_dwordx4 v[64:67], v[6:7], off
	global_load_dwordx4 v[68:71], v[4:5], off
	v_lshl_add_u64 v[4:5], v[80:81], 2, s[4:5]
	v_add_u32_e32 v80, s1, v8
	global_load_dwordx4 v[76:79], v[4:5], off offset:16
	global_load_dwordx4 v[82:85], v[4:5], off
	v_lshlrev_b32_e32 v4, 1, v80
	v_mov_b32_e32 v5, v81
	v_lshl_add_u64 v[6:7], v[2:3], 0, v[4:5]
	v_lshl_add_u64 v[4:5], v[0:1], 0, v[4:5]
	v_readlane_b32 s1, v255, 19
	global_load_dwordx4 v[72:75], v[6:7], off
	global_load_dwordx4 v[102:105], v[4:5], off
	v_lshl_add_u64 v[4:5], v[80:81], 2, s[4:5]
	v_add_u32_e32 v80, s1, v8
	global_load_dwordx4 v[40:43], v[4:5], off offset:16
	global_load_dwordx4 v[44:47], v[4:5], off
	v_lshlrev_b32_e32 v4, 1, v80
	v_mov_b32_e32 v5, v81
	v_lshl_add_u64 v[6:7], v[2:3], 0, v[4:5]
	v_lshl_add_u64 v[4:5], v[0:1], 0, v[4:5]
	v_readlane_b32 s1, v255, 20
	global_load_dwordx4 v[106:109], v[6:7], off
	global_load_dwordx4 v[114:117], v[4:5], off
	v_lshl_add_u64 v[4:5], v[80:81], 2, s[4:5]
	v_add_u32_e32 v80, s1, v8
	global_load_dwordx4 v[32:35], v[4:5], off offset:16
	global_load_dwordx4 v[36:39], v[4:5], off
	v_lshlrev_b32_e32 v4, 1, v80
	v_mov_b32_e32 v5, v81
	v_lshl_add_u64 v[6:7], v[2:3], 0, v[4:5]
	v_lshl_add_u64 v[4:5], v[0:1], 0, v[4:5]
	v_readlane_b32 s1, v255, 21
	global_load_dwordx4 v[118:121], v[6:7], off
	global_load_dwordx4 v[124:127], v[4:5], off
	v_lshl_add_u64 v[4:5], v[80:81], 2, s[4:5]
	v_add_u32_e32 v80, s1, v8
	global_load_dwordx4 v[24:27], v[4:5], off offset:16
	global_load_dwordx4 v[28:31], v[4:5], off
	v_lshlrev_b32_e32 v4, 1, v80
	v_mov_b32_e32 v5, v81
	v_lshl_add_u64 v[6:7], v[2:3], 0, v[4:5]
	v_lshl_add_u64 v[4:5], v[0:1], 0, v[4:5]
	v_readlane_b32 s1, v255, 22
	global_load_dwordx4 v[160:163], v[6:7], off
	global_load_dwordx4 v[164:167], v[4:5], off
	v_lshl_add_u64 v[4:5], v[80:81], 2, s[4:5]
	v_add_u32_e32 v80, s1, v8
	v_lshlrev_b32_e32 v6, 1, v80
	v_mov_b32_e32 v7, v81
	v_lshl_add_u64 v[2:3], v[2:3], 0, v[6:7]
	v_lshl_add_u64 v[0:1], v[0:1], 0, v[6:7]
	v_lshl_add_u64 v[12:13], v[80:81], 2, s[4:5]
	global_load_dwordx4 v[16:19], v[4:5], off offset:16
	global_load_dwordx4 v[20:23], v[4:5], off
	s_nop 0
	global_load_dwordx4 v[4:7], v[2:3], off
	global_load_dwordx4 v[8:11], v[0:1], off
	s_nop 0
	global_load_dwordx4 v[0:3], v[12:13], off offset:16
	s_nop 0
	global_load_dwordx4 v[12:15], v[12:13], off
	s_waitcnt vmcnt(28)
	v_lshlrev_b32_e32 v243, 16, v48
	v_and_b32_e32 v244, 0xffff0000, v48
	v_lshlrev_b32_e32 v48, 16, v52
	v_cndmask_b32_e64 v48, 0, v48, s[2:3]
	v_lshlrev_b32_e32 v219, 16, v49
	v_and_b32_e32 v216, 0xffff0000, v49
	v_and_b32_e32 v49, 0xffff0000, v52
	v_sub_f32_e32 v48, v48, v243
	v_lshlrev_b32_e32 v213, 16, v50
	v_and_b32_e32 v209, 0xffff0000, v50
	v_lshlrev_b32_e32 v205, 16, v51
	v_and_b32_e32 v202, 0xffff0000, v51
	v_lshlrev_b32_e32 v246, 16, v53
	v_and_b32_e32 v245, 0xffff0000, v53
	v_lshlrev_b32_e32 v218, 16, v54
	v_and_b32_e32 v215, 0xffff0000, v54
	v_lshlrev_b32_e32 v212, 16, v55
	v_and_b32_e32 v208, 0xffff0000, v55
	s_waitcnt vmcnt(24)
	s_waitcnt vmcnt(20)
	s_waitcnt vmcnt(16)
	s_waitcnt vmcnt(12)
; __device__ __forceinline__ float sigm(float x) { return __builtin_amdgcn_rcpf(1.0f + __expf(-x)); }
; __device__ __forceinline__ bf16x8_t pack8(const float (&z)[8]) { v4u pw; pw.x = cvtpk(z[0], z[1]); pw.y = cvtpk(z[2], z[3]); pw.z = cvtpk(z[4], z[5]); pw.w = cvtpk(z[6], z[7]); return __builtin_bit_cast(bf16x8_t, pw); }
; __device__ __forceinline__ void unpack8(const v4u w, float (&z)[8]) { z[0] = bflo(w.x); z[1] = bfhi(w.x); z[2] = bflo(w.y); z[3] = bfhi(w.y); z[4] = bflo(w.z); z[5] = bfhi(w.z); z[6] = bflo(w.w); z[7] = bfhi(w.w); }
; template <int ACT> __device__ __forceinline__ bf16x8_t lora_finish(const LoraRaw& r, bool first) {
;     float c[8], p[8];
;     unpack8(r.c, c); unpack8(r.p, p);
;     float z[8];
; #pragma unroll
;     for (int e = 0; e < 8; ++e) { const float mm = e < 4 ? r.m0[e] : r.m1[e - 4]; const float pe = first ? 0.f : p[e]; float v = c[e] + (pe - c[e]) * mm;
;         if (ACT == 1) v = 1.0f - 2.0f * __builtin_amdgcn_rcpf(__expf(2.0f * v) + 1.0f); else if (ACT == 2) v = sigm(v);
;         z[e] = v; }
;     return pack8(z);
; }
; __device__ __forceinline__ void rwkv_p1(const KA& A, const Ctx& F, int l) {
;     ...
;         if (w < 4) {
; #pragma unroll
;             for (int s = 0; s < 8; ++s) xf[s] = lora_finish<2>(lr[s], first);
;         } else {
; #pragma unroll
;             for (int s = 0; s < 4; ++s) { xf[s] = lora_finish<1>(lr[s], first); xf[4 + s] = lora_finish<0>(lr[4 + s], first); }
	v_lshlrev_b32_e32 v156, 16, v106
	v_and_b32_e32 v154, 0xffff0000, v106
	v_lshlrev_b32_e32 v153, 16, v107
	v_and_b32_e32 v150, 0xffff0000, v107
	v_lshlrev_b32_e32 v147, 16, v108
	v_and_b32_e32 v145, 0xffff0000, v108
	v_lshlrev_b32_e32 v139, 16, v109
	v_and_b32_e32 v138, 0xffff0000, v109
	v_lshlrev_b32_e32 v159, 16, v114
	v_and_b32_e32 v158, 0xffff0000, v114
	v_lshlrev_b32_e32 v157, 16, v115
	v_and_b32_e32 v155, 0xffff0000, v115
	v_lshlrev_b32_e32 v152, 16, v116
	v_and_b32_e32 v149, 0xffff0000, v116
	v_lshlrev_b32_e32 v146, 16, v117
	v_and_b32_e32 v142, 0xffff0000, v117
	v_lshlrev_b32_e32 v210, 16, v56
	v_and_b32_e32 v206, 0xffff0000, v56
	v_lshlrev_b32_e32 v204, 16, v57
	v_and_b32_e32 v200, 0xffff0000, v57
	v_lshlrev_b32_e32 v197, 16, v58
	v_and_b32_e32 v195, 0xffff0000, v58
	v_lshlrev_b32_e32 v189, 16, v59
	v_and_b32_e32 v188, 0xffff0000, v59
	v_lshlrev_b32_e32 v217, 16, v60
	v_and_b32_e32 v214, 0xffff0000, v60
	v_lshlrev_b32_e32 v211, 16, v61
	v_and_b32_e32 v207, 0xffff0000, v61
	v_lshlrev_b32_e32 v203, 16, v62
	v_and_b32_e32 v199, 0xffff0000, v62
	v_lshlrev_b32_e32 v196, 16, v63
	v_and_b32_e32 v192, 0xffff0000, v63
	s_waitcnt vmcnt(8)
	v_lshlrev_b32_e32 v143, 16, v118
	v_and_b32_e32 v140, 0xffff0000, v118
	v_lshlrev_b32_e32 v137, 16, v119
	v_and_b32_e32 v134, 0xffff0000, v119
	v_lshlrev_b32_e32 v131, 16, v120
	v_and_b32_e32 v129, 0xffff0000, v120
	v_lshlrev_b32_e32 v123, 16, v121
	v_and_b32_e32 v122, 0xffff0000, v121
	v_lshlrev_b32_e32 v151, 16, v124
	v_and_b32_e32 v148, 0xffff0000, v124
	v_lshlrev_b32_e32 v144, 16, v125
	v_and_b32_e32 v141, 0xffff0000, v125
	v_lshlrev_b32_e32 v136, 16, v126
	v_and_b32_e32 v133, 0xffff0000, v126
	v_lshlrev_b32_e32 v130, 16, v127
	v_and_b32_e32 v126, 0xffff0000, v127
	v_lshlrev_b32_e32 v193, 16, v64
	v_and_b32_e32 v190, 0xffff0000, v64
	v_lshlrev_b32_e32 v187, 16, v65
	v_and_b32_e32 v184, 0xffff0000, v65
	v_lshlrev_b32_e32 v179, 16, v66
	v_and_b32_e32 v177, 0xffff0000, v66
	v_lshlrev_b32_e32 v171, 16, v67
	v_and_b32_e32 v170, 0xffff0000, v67
	v_lshlrev_b32_e32 v201, 16, v68
	v_and_b32_e32 v198, 0xffff0000, v68
	v_lshlrev_b32_e32 v194, 16, v69
	v_and_b32_e32 v191, 0xffff0000, v69
	v_lshlrev_b32_e32 v186, 16, v70
	v_and_b32_e32 v181, 0xffff0000, v70
	v_lshlrev_b32_e32 v178, 16, v71
	v_and_b32_e32 v174, 0xffff0000, v71
	s_waitcnt vmcnt(4)
	v_lshlrev_b32_e32 v127, 16, v160
	v_and_b32_e32 v124, 0xffff0000, v160
	v_lshlrev_b32_e32 v121, 16, v161
	v_and_b32_e32 v119, 0xffff0000, v161
	v_lshlrev_b32_e32 v117, 16, v162
	v_and_b32_e32 v115, 0xffff0000, v162
	v_lshlrev_b32_e32 v113, 16, v163
	v_and_b32_e32 v80, 0xffff0000, v163
	v_lshlrev_b32_e32 v135, 16, v164
	v_and_b32_e32 v132, 0xffff0000, v164
	v_lshlrev_b32_e32 v128, 16, v165
	v_and_b32_e32 v125, 0xffff0000, v165
	v_lshlrev_b32_e32 v120, 16, v166
	v_and_b32_e32 v118, 0xffff0000, v166
	v_lshlrev_b32_e32 v116, 16, v167
	v_and_b32_e32 v114, 0xffff0000, v167
	v_lshlrev_b32_e32 v175, 16, v72
	v_and_b32_e32 v172, 0xffff0000, v72
	v_lshlrev_b32_e32 v169, 16, v73
	v_and_b32_e32 v167, 0xffff0000, v73
	v_lshlrev_b32_e32 v165, 16, v74
	v_and_b32_e32 v163, 0xffff0000, v74
	v_lshlrev_b32_e32 v161, 16, v75
	v_and_b32_e32 v160, 0xffff0000, v75
	v_lshlrev_b32_e32 v185, 16, v102
	v_and_b32_e32 v180, 0xffff0000, v102
	v_lshlrev_b32_e32 v176, 16, v103
	v_and_b32_e32 v173, 0xffff0000, v103
	v_lshlrev_b32_e32 v168, 16, v104
	v_and_b32_e32 v166, 0xffff0000, v104
	v_lshlrev_b32_e32 v164, 16, v105
	v_and_b32_e32 v162, 0xffff0000, v105
	v_fmac_f32_e32 v243, v98, v48
	s_mov_b64 s[4:5], -1
	s_andn2_b64 vcc, exec, s[86:87]
	v_cndmask_b32_e64 v98, 0, v49, s[2:3]
	s_waitcnt vmcnt(0)
	s_cbranch_vccnz .LBB0_390
	v_cndmask_b32_e64 v50, 0, v246, s[2:3]
	v_cndmask_b32_e64 v51, 0, v245, s[2:3]
	v_cndmask_b32_e64 v52, 0, v218, s[2:3]
	v_cndmask_b32_e64 v53, 0, v215, s[2:3]
	v_cndmask_b32_e64 v54, 0, v212, s[2:3]
	v_cndmask_b32_e64 v55, 0, v208, s[2:3]
	v_sub_f32_e32 v49, v98, v244
	v_sub_f32_e32 v50, v50, v219
	v_sub_f32_e32 v51, v51, v216
	v_sub_f32_e32 v52, v52, v213
	v_sub_f32_e32 v53, v53, v209
	v_sub_f32_e32 v54, v54, v205
	v_sub_f32_e32 v55, v55, v202
	v_fma_f32 v49, v99, v49, v244
	v_fma_f32 v50, v100, v50, v219
	v_fma_f32 v51, v101, v51, v216
	v_fma_f32 v52, v94, v52, v213
	v_fma_f32 v53, v95, v53, v209
	v_fma_f32 v54, v96, v54, v205
	v_fma_f32 v55, v97, v55, v202
	v_add_f32_e32 v48, v243, v243
	v_add_f32_e32 v49, v49, v49
	v_add_f32_e32 v50, v50, v50
	v_add_f32_e32 v51, v51, v51
	v_add_f32_e32 v52, v52, v52
	v_add_f32_e32 v53, v53, v53
	v_add_f32_e32 v54, v54, v54
	v_add_f32_e32 v55, v55, v55
	v_mul_f32_e32 v48, 0x3fb8aa3b, v48
	v_mul_f32_e32 v49, 0x3fb8aa3b, v49
	v_mul_f32_e32 v50, 0x3fb8aa3b, v50
	v_mul_f32_e32 v51, 0x3fb8aa3b, v51
	v_mul_f32_e32 v52, 0x3fb8aa3b, v52
	v_mul_f32_e32 v53, 0x3fb8aa3b, v53
	v_mul_f32_e32 v54, 0x3fb8aa3b, v54
	v_mul_f32_e32 v55, 0x3fb8aa3b, v55
	v_exp_f32_e32 v48, v48
	v_exp_f32_e32 v49, v49
	v_exp_f32_e32 v50, v50
	v_exp_f32_e32 v51, v51
	v_exp_f32_e32 v52, v52
	v_exp_f32_e32 v53, v53
	v_exp_f32_e32 v54, v54
	v_exp_f32_e32 v55, v55
	v_add_f32_e32 v48, 1.0, v48
	v_add_f32_e32 v49, 1.0, v49
	v_add_f32_e32 v50, 1.0, v50
	v_add_f32_e32 v51, 1.0, v51
	v_add_f32_e32 v52, 1.0, v52
	v_add_f32_e32 v53, 1.0, v53
	v_add_f32_e32 v54, 1.0, v54
	v_add_f32_e32 v55, 1.0, v55
	v_cndmask_b32_e64 v56, 0, v152, s[2:3]
	v_rcp_f32_e32 v48, v48
	v_rcp_f32_e32 v49, v49
	v_rcp_f32_e32 v50, v50
	v_rcp_f32_e32 v51, v51
	v_rcp_f32_e32 v52, v52
	v_rcp_f32_e32 v53, v53
	v_rcp_f32_e32 v54, v54
	v_rcp_f32_e32 v55, v55
	v_sub_f32_e32 v56, v56, v147
	v_fma_f32 v58, v32, v56, v147
	v_cndmask_b32_e64 v56, 0, v149, s[2:3]
	v_sub_f32_e32 v56, v56, v145
	v_fma_f32 v59, v33, v56, v145
; __device__ __forceinline__ float sigm(float x) { return __builtin_amdgcn_rcpf(1.0f + __expf(-x)); }
; __device__ __forceinline__ bf16x8_t pack8(const float (&z)[8]) { v4u pw; pw.x = cvtpk(z[0], z[1]); pw.y = cvtpk(z[2], z[3]); pw.z = cvtpk(z[4], z[5]); pw.w = cvtpk(z[6], z[7]); return __builtin_bit_cast(bf16x8_t, pw); }
; __device__ __forceinline__ void unpack8(const v4u w, float (&z)[8]) { z[0] = bflo(w.x); z[1] = bfhi(w.x); z[2] = bflo(w.y); z[3] = bfhi(w.y); z[4] = bflo(w.z); z[5] = bfhi(w.z); z[6] = bflo(w.w); z[7] = bfhi(w.w); }
; template <int ACT> __device__ __forceinline__ bf16x8_t lora_finish(const LoraRaw& r, bool first) {
;     float c[8], p[8];
;     unpack8(r.c, c); unpack8(r.p, p);
;     float z[8];
; #pragma unroll
;     for (int e = 0; e < 8; ++e) { const float mm = e < 4 ? r.m0[e] : r.m1[e - 4]; const float pe = first ? 0.f : p[e]; float v = c[e] + (pe - c[e]) * mm;
;         if (ACT == 1) v = 1.0f - 2.0f * __builtin_amdgcn_rcpf(__expf(2.0f * v) + 1.0f); else if (ACT == 2) v = sigm(v);
;         z[e] = v; }
;     return pack8(z);
; }
; __device__ __forceinline__ void rwkv_p1(const KA& A, const Ctx& F, int l) {
;     ...
;             for (int s = 0; s < 4; ++s) { xf[s] = lora_finish<1>(lr[s], first); xf[4 + s] = lora_finish<0>(lr[4 + s], first); }
	v_cndmask_b32_e64 v56, 0, v146, s[2:3]
	v_pk_fma_f32 v[48:49], v[48:49], 2.0, 1.0 op_sel_hi:[1,0,0] neg_lo:[1,0,0] neg_hi:[1,0,0]
	v_pk_fma_f32 v[50:51], v[50:51], 2.0, 1.0 op_sel_hi:[1,0,0] neg_lo:[1,0,0] neg_hi:[1,0,0]
	v_pk_fma_f32 v[52:53], v[52:53], 2.0, 1.0 op_sel_hi:[1,0,0] neg_lo:[1,0,0] neg_hi:[1,0,0]
	v_pk_fma_f32 v[54:55], v[54:55], 2.0, 1.0 op_sel_hi:[1,0,0] neg_lo:[1,0,0] neg_hi:[1,0,0]
	v_sub_f32_e32 v56, v56, v139
	v_cvt_pk_bf16_f32 v48, v48, v49
	v_cvt_pk_bf16_f32 v49, v50, v51
	v_cvt_pk_bf16_f32 v50, v52, v53
	v_cvt_pk_bf16_f32 v51, v54, v55
	v_cndmask_b32_e64 v52, 0, v159, s[2:3]
	v_cndmask_b32_e64 v53, 0, v158, s[2:3]
	v_cndmask_b32_e64 v54, 0, v157, s[2:3]
	v_cndmask_b32_e64 v55, 0, v155, s[2:3]
	v_fma_f32 v60, v34, v56, v139
	v_cndmask_b32_e64 v56, 0, v142, s[2:3]
	v_sub_f32_e32 v52, v52, v156
	v_sub_f32_e32 v53, v53, v154
	v_sub_f32_e32 v54, v54, v153
	v_sub_f32_e32 v55, v55, v150
	v_sub_f32_e32 v56, v56, v138
	v_fma_f32 v52, v36, v52, v156
	v_fma_f32 v53, v37, v53, v154
	v_fma_f32 v54, v38, v54, v153
	v_fma_f32 v55, v39, v55, v150
	v_fma_f32 v61, v35, v56, v138
	v_cvt_pk_bf16_f32 v56, v52, v53
	v_cvt_pk_bf16_f32 v57, v54, v55
	v_cvt_pk_bf16_f32 v58, v58, v59
	v_cndmask_b32_e64 v52, 0, v217, s[2:3]
	v_cndmask_b32_e64 v53, 0, v214, s[2:3]
	v_cvt_pk_bf16_f32 v59, v60, v61
	v_cndmask_b32_e64 v54, 0, v211, s[2:3]
	v_cndmask_b32_e64 v55, 0, v207, s[2:3]
	v_cndmask_b32_e64 v60, 0, v203, s[2:3]
	v_cndmask_b32_e64 v61, 0, v199, s[2:3]
	v_cndmask_b32_e64 v62, 0, v196, s[2:3]
	v_cndmask_b32_e64 v63, 0, v192, s[2:3]
	v_sub_f32_e32 v52, v52, v210
	v_sub_f32_e32 v53, v53, v206
	v_sub_f32_e32 v54, v54, v204
	v_sub_f32_e32 v55, v55, v200
	v_sub_f32_e32 v60, v60, v197
	v_sub_f32_e32 v61, v61, v195
	v_sub_f32_e32 v62, v62, v189
	v_sub_f32_e32 v63, v63, v188
	v_fma_f32 v52, v90, v52, v210
	v_fma_f32 v53, v91, v53, v206
	v_fma_f32 v54, v92, v54, v204
	v_fma_f32 v55, v93, v55, v200
	v_fma_f32 v60, v86, v60, v197
	v_fma_f32 v61, v87, v61, v195
	v_fma_f32 v62, v88, v62, v189
	v_fma_f32 v63, v89, v63, v188
	v_add_f32_e32 v52, v52, v52
	v_add_f32_e32 v53, v53, v53
	v_add_f32_e32 v54, v54, v54
	v_add_f32_e32 v55, v55, v55
	v_add_f32_e32 v60, v60, v60
	v_add_f32_e32 v61, v61, v61
	v_add_f32_e32 v62, v62, v62
	v_add_f32_e32 v63, v63, v63
	v_mul_f32_e32 v52, 0x3fb8aa3b, v52
	v_mul_f32_e32 v53, 0x3fb8aa3b, v53
	v_mul_f32_e32 v54, 0x3fb8aa3b, v54
	v_mul_f32_e32 v55, 0x3fb8aa3b, v55
	v_mul_f32_e32 v60, 0x3fb8aa3b, v60
	v_mul_f32_e32 v61, 0x3fb8aa3b, v61
	v_mul_f32_e32 v62, 0x3fb8aa3b, v62
	v_mul_f32_e32 v63, 0x3fb8aa3b, v63
	v_exp_f32_e32 v52, v52
	v_exp_f32_e32 v53, v53
	v_exp_f32_e32 v54, v54
	v_exp_f32_e32 v55, v55
	v_exp_f32_e32 v60, v60
	v_exp_f32_e32 v61, v61
	v_exp_f32_e32 v62, v62
	v_exp_f32_e32 v63, v63
	v_add_f32_e32 v52, 1.0, v52
	v_add_f32_e32 v53, 1.0, v53
	v_add_f32_e32 v54, 1.0, v54
	v_add_f32_e32 v55, 1.0, v55
	v_add_f32_e32 v60, 1.0, v60
	v_add_f32_e32 v61, 1.0, v61
	v_add_f32_e32 v62, 1.0, v62
	v_add_f32_e32 v63, 1.0, v63
	v_cndmask_b32_e64 v64, 0, v136, s[2:3]
	v_rcp_f32_e32 v52, v52
	v_rcp_f32_e32 v53, v53
	v_rcp_f32_e32 v54, v54
	v_rcp_f32_e32 v55, v55
	v_rcp_f32_e32 v60, v60
	v_rcp_f32_e32 v61, v61
	v_rcp_f32_e32 v62, v62
	v_rcp_f32_e32 v63, v63
	v_sub_f32_e32 v64, v64, v131
	v_fma_f32 v66, v24, v64, v131
	v_cndmask_b32_e64 v64, 0, v133, s[2:3]
	v_sub_f32_e32 v64, v64, v129
	v_fma_f32 v67, v25, v64, v129
	v_cndmask_b32_e64 v64, 0, v130, s[2:3]
	v_pk_fma_f32 v[52:53], v[52:53], 2.0, 1.0 op_sel_hi:[1,0,0] neg_lo:[1,0,0] neg_hi:[1,0,0]
	v_pk_fma_f32 v[54:55], v[54:55], 2.0, 1.0 op_sel_hi:[1,0,0] neg_lo:[1,0,0] neg_hi:[1,0,0]
	v_pk_fma_f32 v[60:61], v[60:61], 2.0, 1.0 op_sel_hi:[1,0,0] neg_lo:[1,0,0] neg_hi:[1,0,0]
	v_pk_fma_f32 v[62:63], v[62:63], 2.0, 1.0 op_sel_hi:[1,0,0] neg_lo:[1,0,0] neg_hi:[1,0,0]
	v_sub_f32_e32 v64, v64, v123
	v_cvt_pk_bf16_f32 v52, v52, v53
	v_cvt_pk_bf16_f32 v53, v54, v55
	v_cvt_pk_bf16_f32 v54, v60, v61
	v_cvt_pk_bf16_f32 v55, v62, v63
	v_cndmask_b32_e64 v60, 0, v151, s[2:3]
	v_cndmask_b32_e64 v61, 0, v148, s[2:3]
	v_cndmask_b32_e64 v62, 0, v144, s[2:3]
	v_cndmask_b32_e64 v63, 0, v141, s[2:3]
	v_fma_f32 v68, v26, v64, v123
	v_cndmask_b32_e64 v64, 0, v126, s[2:3]
	v_sub_f32_e32 v60, v60, v143
	v_sub_f32_e32 v61, v61, v140
	v_sub_f32_e32 v62, v62, v137
	v_sub_f32_e32 v63, v63, v134
	v_sub_f32_e32 v64, v64, v122
	v_fma_f32 v60, v28, v60, v143
	v_fma_f32 v61, v29, v61, v140
	v_fma_f32 v62, v30, v62, v137
	v_fma_f32 v63, v31, v63, v134
	v_fma_f32 v69, v27, v64, v122
	v_cvt_pk_bf16_f32 v64, v60, v61
	v_cvt_pk_bf16_f32 v65, v62, v63
	v_cvt_pk_bf16_f32 v66, v66, v67
	v_cndmask_b32_e64 v60, 0, v201, s[2:3]
	v_cndmask_b32_e64 v61, 0, v198, s[2:3]
	v_cvt_pk_bf16_f32 v67, v68, v69
	v_cndmask_b32_e64 v62, 0, v194, s[2:3]
	v_cndmask_b32_e64 v63, 0, v191, s[2:3]
	v_cndmask_b32_e64 v68, 0, v186, s[2:3]
	v_cndmask_b32_e64 v69, 0, v181, s[2:3]
	v_cndmask_b32_e64 v70, 0, v178, s[2:3]
	v_cndmask_b32_e64 v71, 0, v174, s[2:3]
	v_sub_f32_e32 v60, v60, v193
	v_sub_f32_e32 v61, v61, v190
	v_sub_f32_e32 v62, v62, v187
	v_sub_f32_e32 v63, v63, v184
	v_sub_f32_e32 v68, v68, v179
	v_sub_f32_e32 v69, v69, v177
	v_sub_f32_e32 v70, v70, v171
	v_sub_f32_e32 v71, v71, v170
	v_fma_f32 v60, v82, v60, v193
	v_fma_f32 v61, v83, v61, v190
	v_fma_f32 v62, v84, v62, v187
	v_fma_f32 v63, v85, v63, v184
	v_fma_f32 v68, v76, v68, v179
	v_fma_f32 v69, v77, v69, v177
	v_fma_f32 v70, v78, v70, v171
	v_fma_f32 v71, v79, v71, v170
	v_add_f32_e32 v60, v60, v60
	v_add_f32_e32 v61, v61, v61
	v_add_f32_e32 v62, v62, v62
	v_add_f32_e32 v63, v63, v63
	v_add_f32_e32 v68, v68, v68
	v_add_f32_e32 v69, v69, v69
	v_add_f32_e32 v70, v70, v70
	v_add_f32_e32 v71, v71, v71
; __device__ __forceinline__ float sigm(float x) { return __builtin_amdgcn_rcpf(1.0f + __expf(-x)); }
; __device__ __forceinline__ bf16x8_t pack8(const float (&z)[8]) { v4u pw; pw.x = cvtpk(z[0], z[1]); pw.y = cvtpk(z[2], z[3]); pw.z = cvtpk(z[4], z[5]); pw.w = cvtpk(z[6], z[7]); return __builtin_bit_cast(bf16x8_t, pw); }
; __device__ __forceinline__ void unpack8(const v4u w, float (&z)[8]) { z[0] = bflo(w.x); z[1] = bfhi(w.x); z[2] = bflo(w.y); z[3] = bfhi(w.y); z[4] = bflo(w.z); z[5] = bfhi(w.z); z[6] = bflo(w.w); z[7] = bfhi(w.w); }
; template <int ACT> __device__ __forceinline__ bf16x8_t lora_finish(const LoraRaw& r, bool first) {
;     float c[8], p[8];
;     unpack8(r.c, c); unpack8(r.p, p);
;     float z[8];
; #pragma unroll
;     for (int e = 0; e < 8; ++e) { const float mm = e < 4 ? r.m0[e] : r.m1[e - 4]; const float pe = first ? 0.f : p[e]; float v = c[e] + (pe - c[e]) * mm;
;         if (ACT == 1) v = 1.0f - 2.0f * __builtin_amdgcn_rcpf(__expf(2.0f * v) + 1.0f); else if (ACT == 2) v = sigm(v);
;         z[e] = v; }
;     return pack8(z);
; }
; __device__ __forceinline__ void rwkv_p1(const KA& A, const Ctx& F, int l) {
;     ...
;             for (int s = 0; s < 4; ++s) { xf[s] = lora_finish<1>(lr[s], first); xf[4 + s] = lora_finish<0>(lr[4 + s], first); }
	v_mul_f32_e32 v60, 0x3fb8aa3b, v60
	v_mul_f32_e32 v61, 0x3fb8aa3b, v61
	v_mul_f32_e32 v62, 0x3fb8aa3b, v62
	v_mul_f32_e32 v63, 0x3fb8aa3b, v63
	v_mul_f32_e32 v68, 0x3fb8aa3b, v68
	v_mul_f32_e32 v69, 0x3fb8aa3b, v69
	v_mul_f32_e32 v70, 0x3fb8aa3b, v70
	v_mul_f32_e32 v71, 0x3fb8aa3b, v71
	v_exp_f32_e32 v60, v60
	v_exp_f32_e32 v61, v61
	v_exp_f32_e32 v62, v62
	v_exp_f32_e32 v63, v63
	v_exp_f32_e32 v68, v68
	v_exp_f32_e32 v69, v69
	v_exp_f32_e32 v70, v70
	v_exp_f32_e32 v71, v71
	v_add_f32_e32 v60, 1.0, v60
	v_add_f32_e32 v61, 1.0, v61
	v_add_f32_e32 v62, 1.0, v62
	v_add_f32_e32 v63, 1.0, v63
	v_add_f32_e32 v68, 1.0, v68
	v_add_f32_e32 v69, 1.0, v69
	v_add_f32_e32 v70, 1.0, v70
	v_add_f32_e32 v71, 1.0, v71
	v_cndmask_b32_e64 v72, 0, v120, s[2:3]
	v_rcp_f32_e32 v60, v60
	v_rcp_f32_e32 v61, v61
	v_rcp_f32_e32 v62, v62
	v_rcp_f32_e32 v63, v63
	v_rcp_f32_e32 v68, v68
	v_rcp_f32_e32 v69, v69
	v_rcp_f32_e32 v70, v70
	v_rcp_f32_e32 v71, v71
	v_sub_f32_e32 v72, v72, v117
	v_fma_f32 v74, v16, v72, v117
	v_cndmask_b32_e64 v72, 0, v118, s[2:3]
	v_sub_f32_e32 v72, v72, v115
	v_fma_f32 v75, v17, v72, v115
	v_cndmask_b32_e64 v72, 0, v116, s[2:3]
	v_pk_fma_f32 v[60:61], v[60:61], 2.0, 1.0 op_sel_hi:[1,0,0] neg_lo:[1,0,0] neg_hi:[1,0,0]
	v_pk_fma_f32 v[62:63], v[62:63], 2.0, 1.0 op_sel_hi:[1,0,0] neg_lo:[1,0,0] neg_hi:[1,0,0]
	v_pk_fma_f32 v[68:69], v[68:69], 2.0, 1.0 op_sel_hi:[1,0,0] neg_lo:[1,0,0] neg_hi:[1,0,0]
	v_pk_fma_f32 v[70:71], v[70:71], 2.0, 1.0 op_sel_hi:[1,0,0] neg_lo:[1,0,0] neg_hi:[1,0,0]
	v_sub_f32_e32 v72, v72, v113
	v_cvt_pk_bf16_f32 v60, v60, v61
	v_cvt_pk_bf16_f32 v61, v62, v63
	v_cvt_pk_bf16_f32 v62, v68, v69
	v_cvt_pk_bf16_f32 v63, v70, v71
	v_cndmask_b32_e64 v68, 0, v135, s[2:3]
	v_cndmask_b32_e64 v69, 0, v132, s[2:3]
	v_cndmask_b32_e64 v70, 0, v128, s[2:3]
	v_cndmask_b32_e64 v71, 0, v125, s[2:3]
	v_fma_f32 v102, v18, v72, v113
	v_cndmask_b32_e64 v72, 0, v114, s[2:3]
	v_sub_f32_e32 v68, v68, v127
	v_sub_f32_e32 v69, v69, v124
	v_sub_f32_e32 v70, v70, v121
	v_sub_f32_e32 v71, v71, v119
	v_sub_f32_e32 v72, v72, v80
	v_fma_f32 v68, v20, v68, v127
	v_fma_f32 v69, v21, v69, v124
	v_fma_f32 v70, v22, v70, v121
	v_fma_f32 v71, v23, v71, v119
	v_fma_f32 v103, v19, v72, v80
	v_cvt_pk_bf16_f32 v72, v68, v69
	v_cvt_pk_bf16_f32 v73, v70, v71
	v_cvt_pk_bf16_f32 v74, v74, v75
	v_cndmask_b32_e64 v68, 0, v185, s[2:3]
	v_cndmask_b32_e64 v69, 0, v180, s[2:3]
	v_cvt_pk_bf16_f32 v75, v102, v103
	v_cndmask_b32_e64 v70, 0, v176, s[2:3]
	v_cndmask_b32_e64 v71, 0, v173, s[2:3]
	v_cndmask_b32_e64 v102, 0, v168, s[2:3]
	v_cndmask_b32_e64 v103, 0, v166, s[2:3]
	v_sub_f32_e32 v68, v68, v175
	v_sub_f32_e32 v69, v69, v172
	v_sub_f32_e32 v70, v70, v169
	v_sub_f32_e32 v71, v71, v167
	v_sub_f32_e32 v102, v102, v165
	v_sub_f32_e32 v103, v103, v163
	v_fma_f32 v68, v44, v68, v175
	v_fma_f32 v69, v45, v69, v172
	v_fma_f32 v70, v46, v70, v169
	v_fma_f32 v71, v47, v71, v167
	v_fma_f32 v102, v40, v102, v165
	v_fma_f32 v103, v41, v103, v163
	v_add_f32_e32 v68, v68, v68
	v_add_f32_e32 v69, v69, v69
	v_add_f32_e32 v70, v70, v70
	v_add_f32_e32 v71, v71, v71
	v_add_f32_e32 v102, v102, v102
	v_add_f32_e32 v103, v103, v103
	v_mul_f32_e32 v68, 0x3fb8aa3b, v68
	v_mul_f32_e32 v69, 0x3fb8aa3b, v69
	v_mul_f32_e32 v70, 0x3fb8aa3b, v70
	v_mul_f32_e32 v71, 0x3fb8aa3b, v71
	v_mul_f32_e32 v102, 0x3fb8aa3b, v102
	v_mul_f32_e32 v103, 0x3fb8aa3b, v103
	v_cndmask_b32_e64 v104, 0, v164, s[2:3]
	v_cndmask_b32_e64 v105, 0, v162, s[2:3]
	v_exp_f32_e32 v68, v68
	v_exp_f32_e32 v69, v69
	v_exp_f32_e32 v70, v70
	v_exp_f32_e32 v71, v71
	v_exp_f32_e32 v102, v102
	v_exp_f32_e32 v103, v103
	v_sub_f32_e32 v104, v104, v161
	v_sub_f32_e32 v105, v105, v160
	v_fma_f32 v104, v42, v104, v161
	v_fma_f32 v105, v43, v105, v160
	v_add_f32_e32 v104, v104, v104
	v_add_f32_e32 v105, v105, v105
	v_mul_f32_e32 v104, 0x3fb8aa3b, v104
	v_mul_f32_e32 v105, 0x3fb8aa3b, v105
	v_add_f32_e32 v68, 1.0, v68
	v_add_f32_e32 v69, 1.0, v69
	v_add_f32_e32 v70, 1.0, v70
	v_add_f32_e32 v71, 1.0, v71
	v_add_f32_e32 v102, 1.0, v102
	v_add_f32_e32 v103, 1.0, v103
	v_exp_f32_e32 v104, v104
	v_exp_f32_e32 v105, v105
	v_rcp_f32_e32 v68, v68
	v_rcp_f32_e32 v69, v69
	v_rcp_f32_e32 v70, v70
	v_rcp_f32_e32 v71, v71
	v_rcp_f32_e32 v102, v102
	v_rcp_f32_e32 v103, v103
	v_add_f32_e32 v104, 1.0, v104
	v_add_f32_e32 v105, 1.0, v105
	v_rcp_f32_e32 v104, v104
	v_rcp_f32_e32 v105, v105
	v_pk_fma_f32 v[68:69], v[68:69], 2.0, 1.0 op_sel_hi:[1,0,0] neg_lo:[1,0,0] neg_hi:[1,0,0]
	v_pk_fma_f32 v[70:71], v[70:71], 2.0, 1.0 op_sel_hi:[1,0,0] neg_lo:[1,0,0] neg_hi:[1,0,0]
	v_pk_fma_f32 v[102:103], v[102:103], 2.0, 1.0 op_sel_hi:[1,0,0] neg_lo:[1,0,0] neg_hi:[1,0,0]
	v_cvt_pk_bf16_f32 v68, v68, v69
	v_cvt_pk_bf16_f32 v69, v70, v71
	v_cvt_pk_bf16_f32 v70, v102, v103
	v_lshlrev_b32_e32 v102, 16, v8
	v_cndmask_b32_e64 v103, 0, v102, s[2:3]
	v_lshlrev_b32_e32 v102, 16, v4
	v_sub_f32_e32 v103, v103, v102
	v_pk_fma_f32 v[104:105], v[104:105], 2.0, 1.0 op_sel_hi:[1,0,0] neg_lo:[1,0,0] neg_hi:[1,0,0]
	v_fmac_f32_e32 v102, v12, v103
	v_and_b32_e32 v103, 0xffff0000, v8
	v_cvt_pk_bf16_f32 v71, v104, v105
	v_cndmask_b32_e64 v104, 0, v103, s[2:3]
	v_and_b32_e32 v103, 0xffff0000, v4
	v_sub_f32_e32 v104, v104, v103
	v_fmac_f32_e32 v103, v13, v104
	v_lshlrev_b32_e32 v104, 16, v9
	v_cndmask_b32_e64 v105, 0, v104, s[2:3]
	v_lshlrev_b32_e32 v104, 16, v5
	v_sub_f32_e32 v105, v105, v104
	v_fmac_f32_e32 v104, v14, v105
	v_and_b32_e32 v105, 0xffff0000, v9
	v_cndmask_b32_e64 v106, 0, v105, s[2:3]
	v_and_b32_e32 v105, 0xffff0000, v5
	v_sub_f32_e32 v106, v106, v105
	v_fmac_f32_e32 v105, v15, v106
	v_lshlrev_b32_e32 v106, 16, v10
	v_cndmask_b32_e64 v107, 0, v106, s[2:3]
	v_lshlrev_b32_e32 v106, 16, v6
	v_sub_f32_e32 v107, v107, v106
	v_fmac_f32_e32 v106, v0, v107
	v_and_b32_e32 v107, 0xffff0000, v10
	v_cndmask_b32_e64 v108, 0, v107, s[2:3]
	v_and_b32_e32 v107, 0xffff0000, v6
	v_sub_f32_e32 v108, v108, v107
	v_fmac_f32_e32 v107, v1, v108
	v_lshlrev_b32_e32 v108, 16, v11
	v_cndmask_b32_e64 v109, 0, v108, s[2:3]
	v_lshlrev_b32_e32 v108, 16, v7
	v_sub_f32_e32 v109, v109, v108
	v_and_b32_e32 v222, 0xffff0000, v11
	v_fmac_f32_e32 v108, v2, v109
	v_and_b32_e32 v109, 0xffff0000, v7
	v_cndmask_b32_e64 v222, 0, v222, s[2:3]
	v_sub_f32_e32 v222, v222, v109
	v_fmac_f32_e32 v109, v3, v222
	s_mov_b64 s[4:5], 0

;     __device__ __forceinline__ const float* in(int i) const { return *(const __attribute__((address_space(4))) cfptr_t*)(p + 8 * i); }
; __device__ __forceinline__ void rwkv_p1(const KA& A, const Ctx& F, int l) {
;     ...
;         const int item = (b * 6 + h) * 64 + j;
;         int hc = h * 64 + lane;
;         float rr[8], kn[8], vv[8], kk[8], bb[8], eadd[8], lp[8]; unsigned bhp[4], khp[4];
;         bf16 rw_p[3], rw_c[8][3];
;         { const bf16* pp = (w == 0) ? (BRB + (size_t)(b * 64 + (j > 0 ? j - 1 : 0)) * PSW + C_RW + hc) : (PS + (row0 + 8 * w - 1) * PSW + C_RW + hc);
;           rw_p[0] = pp[0]; rw_p[1] = pp[384]; rw_p[2] = pp[768];
;           if (w == 0 && j == 0) { rw_p[0] = 0; rw_p[1] = 0; rw_p[2] = 0; }
; #pragma unroll
;           for (int i = 0; i < 8; ++i) { const bf16* cp = PS + (row0 + 8 * w + i) * PSW + C_RW + hc; rw_c[i][0] = cp[0]; rw_c[i][1] = cp[384]; rw_c[i][2] = cp[768]; } }
;         const float mr = mix[hc], mk = mix[384 + hc], mv = mix[768 + hc];
;         const float w0c = A.in(4)[l * 384 + hc], a0c = A.in(6)[l * 384 + hc], kkc = A.in(9)[l * 384 + hc], kac = A.in(10)[l * 384 + hc], rkc = A.in(11)[l * 384 + hc];
.LBB0_392:
	s_mul_i32 s0, s0, 6
	v_writelane_b32 v255, s0, 36
	v_readlane_b32 s0, v254, 6
	v_readlane_b32 s6, v254, 0
	s_or_b32 s0, s6, s0
	s_cmp_eq_u32 s0, 0
	v_readlane_b32 s2, v254, 34
	v_readlane_b32 s3, v255, 33
	v_readlane_b32 s4, v255, 34
	s_cselect_b64 s[0:1], -1, 0
	s_add_u32 s2, s3, s2
	v_readlane_b32 s3, v254, 19
	v_readlane_b32 s5, v255, 35
	s_addc_u32 s3, s5, s3
	s_mulk_i32 s3, 0x1600
	s_mul_hi_u32 s4, s2, 0x1600
	s_add_i32 s4, s4, s3
	s_mulk_i32 s2, 0x1600
	s_add_u32 s88, s82, s2
	s_addc_u32 s89, s83, s4
	s_mov_b32 s2, s80
	s_add_u32 s4, s88, 0xfffff300
	v_writelane_b32 v255, s2, 38
	v_sub_u32_e64 v0, s6, 1 clamp
	s_addc_u32 s5, s89, -1
	v_writelane_b32 v255, s3, 39
	s_and_b32 s2, s80, 7
	s_lshl_b32 s2, s2, 6
	v_readfirstlane_b32 s3, v0
	v_readlane_b32 s8, v253, 60
	s_or_b32 s2, s3, s2
	v_readlane_b32 s10, v253, 62
	v_readlane_b32 s11, v253, 63
	s_mul_hi_i32 s3, s2, 0x1600
	s_mulk_i32 s2, 0x1600
	s_mov_b64 s[6:7], s[10:11]
	s_add_u32 s2, s6, s2
	s_addc_u32 s3, s7, s3
	s_add_u32 s6, s2, 0x1a500900
	s_addc_u32 s7, s3, 0
	v_readlane_b32 s2, v254, 15
	v_readlane_b32 s3, v254, 16
	s_and_b64 s[2:3], s[2:3], exec
	s_cselect_b32 s3, s7, s5
	s_cselect_b32 s2, s6, s4
	v_writelane_b32 v255, s2, 40
	v_cvt_pk_bf16_f32 v76, v102, v103
	v_cvt_pk_bf16_f32 v77, v104, v105
	v_writelane_b32 v255, s3, 41
	s_add_u32 s2, s88, 0x1f00
	s_addc_u32 s3, s89, 0
	v_writelane_b32 v255, s2, 42
	v_cvt_pk_bf16_f32 v78, v106, v107
	v_cvt_pk_bf16_f32 v79, v108, v109
	v_writelane_b32 v255, s3, 43
	s_add_u32 s2, s88, 0x3500
	s_addc_u32 s3, s89, 0
	v_writelane_b32 v255, s2, 44
	s_mov_b32 s18, 0
	v_readlane_b32 s9, v253, 61
	v_writelane_b32 v255, s3, 45
	s_add_u32 s2, s88, 0x4b00
	s_addc_u32 s3, s89, 0
	s_add_u32 s34, s88, 0x6100
	s_addc_u32 s35, s89, 0
	s_add_u32 s16, s88, 0x7700
	s_addc_u32 s17, s89, 0
	s_add_u32 s38, s88, 0x8d00
	s_addc_u32 s39, s89, 0
	s_add_u32 s92, s88, 0xa300
	s_addc_u32 s93, s89, 0
	s_add_u32 s94, s88, 0x2500
	s_addc_u32 s95, s89, 0
	s_add_u32 s96, s88, 0x3b00
	s_addc_u32 s97, s89, 0
	s_add_u32 s84, s88, 0x5100
	s_addc_u32 s85, s89, 0
	v_writelane_b32 v255, s2, 46
	s_add_u32 s40, s88, 0x6700
	s_addc_u32 s41, s89, 0
	v_writelane_b32 v255, s3, 47
	v_readlane_b32 s2, v253, 58
	s_add_u32 s44, s88, 0x7d00
	v_readlane_b32 s3, v253, 59
	s_addc_u32 s45, s89, 0
	s_load_dwordx8 s[76:83], s[2:3], 0x48
	s_add_u32 s46, s88, 0x9300
	s_addc_u32 s47, s89, 0
	s_add_u32 s48, s88, 0xa900
	s_addc_u32 s49, s89, 0
	s_branch .LBB0_394

; __global__ void __launch_bounds__(NTHREADS, 2) mega_fwd(Args args) {
;     ...
;         if (ph + 1 < args.ph_hi) {
;     ...
;             for (int e_ = 0; e_ < EXTRA_SYNCS; ++e_) { XcdBarrier b2 = bar; asm volatile("" : "+s"(b2.bar)); int tb_; asm volatile("v_mbcnt_lo_u32_b32 %0, -1, 0\n\tv_mbcnt_hi_u32_b32 %0, -1, %0\n\tv_or_b32 %0, %1, %0" : "=&v"(tb_) : "s"(wv0 << 6)); xcd_barrier(b2, tb_); }
;     ...
;             if (args.ph_lo < 0) { __threadfence(); cg::this_grid().sync(); }
;             { XcdBarrier b2 = bar; asm volatile("" : "+s"(b2.bar)); int tb_; asm volatile("v_mbcnt_lo_u32_b32 %0, -1, 0\n\tv_mbcnt_hi_u32_b32 %0, -1, %0\n\tv_or_b32 %0, %1, %0" : "=&v"(tb_) : "s"(wv0 << 6)); xcd_barrier(b2, tb_); } }
.LBB0_552:
	s_andn2_saveexec_b64 s[4:5], s[4:5]
	s_cbranch_execz .LBB0_8
	s_add_i32 s4, s70, -2
	s_cmp_lt_u32 s4, 15
	s_cbranch_scc0 .Lxb_global
	s_lshr_b32 s5, 0x4161, s4
	s_and_b32 s5, s5, 1
	s_cbranch_scc0 .Lxb_global
	v_readfirstlane_b32 s5, v18
	s_cmp_eq_u32 s5, 0
	s_cbranch_scc0 .Lxb_global
	s_mov_b64 s[0:1], exec
	s_branch .LBB0_7
